# placement check: post-P0 instruction stream shifted by +32 bytes
# baseline (speedup 1.0000x reference)
; __global__ void __launch_bounds__(512, 2) fwd_megakernel(Args args) {
;     ...
;     float* MOD = (float*)(ws + WS_MOD); float* CTXS = (float*)(ws + WS_CTXS);
;     bf16_t* W256 = (bf16_t*)(ws + WS_W256); bf16_t* CS256 = (bf16_t*)(ws + WS_CS256); float* AT = (float*)(ws + WS_AT);
;     bf16_t* WINT = (bf16_t*)(ws + WS_WINT); bf16_t* WOUTT = (bf16_t*)(ws + WS_WOUTT); bf16_t* WGLUT = (bf16_t*)(ws + WS_WGLUT); bf16_t* WFT = (bf16_t*)(ws + WS_WFT);
;     bf16_t* W13T = (bf16_t*)(ws + WS_W13T); bf16_t* W2T = (bf16_t*)(ws + WS_W2T); bf16_t* TC = (bf16_t*)(ws + WS_TC); bf16_t* BS = (bf16_t*)(ws + WS_BS);
;     ...
;         const Ctx X = mkctx(lds);
;         float* scr = (float*)(lds + X.wave * 16384);
;         constexpr int I13 = 16 * 88, I2 = 44 * 32, IIN = 16 * 40, IO = 16 * 32, IG = 8 * 16;
;         constexpr int NITEMS = 8 * I13 + 4 * I2 + IIN + IO + IG + IO;
;         const bool ssmblk = X.G >= 64 && X.bx >= X.G - 32;
;         const int GW = X.G >= 64 ? X.G - 32 : X.G;
;         if (!ssmblk) {
;         for (int it = X.gw; it < NITEMS; it += GW * 8) {
;             int r = it;
;             if (r < 8 * I13) { const int which = r / (4 * I13); r %= 4 * I13; const int lh = r / I13; r %= I13;
;                 if (which == 0) tr_item<1>(args.in[7] + (size_t)lh * D * FF, D, FF, W13T + (size_t)lh * NUP * D, scr, r, X.lane);
;                 else tr_item<2>(args.in[8] + (size_t)lh * D * FF, D, FF, W13T + (size_t)lh * NUP * D, scr, r, X.lane);
;                 continue; }
;             r -= 8 * I13;
;             if (r < 4 * I2) { const int lh = r / I2; r %= I2; tr_item<0>(args.in[9] + (size_t)lh * FF * D, FF, D, W2T + (size_t)lh * D * FF, scr, r, X.lane); continue; }
;             r -= 4 * I2;
;             if (r < IIN) { tr_item<0>(args.in[10], D, INW, WINT, scr, r, X.lane); continue; } r -= IIN;
;             if (r < IO) { tr_item<0>(args.in[23], D, D, WOUTT, scr, r, X.lane); continue; } r -= IO;
;             if (r < IG) { tr_item<0>(args.in[22], 512, 512, WGLUT, scr, r, X.lane); continue; } r -= IG;
;             tr_item<0>(args.in[24], D, D, WFT, scr, r, X.lane);
;         }
.LBB0_6:
	s_nop 0
	s_nop 0
	s_nop 0
	s_nop 0
	s_nop 0
	s_nop 0
	s_nop 0
	s_nop 0
	s_load_dwordx16 s[36:51], s[0:1], 0x0
	s_add_u32 s0, s88, 0xa00000
	v_writelane_b32 v254, s8, 2
	s_addc_u32 s1, s89, 0
	s_add_u32 s96, s88, 0xb00000
	v_writelane_b32 v254, s9, 3
	v_writelane_b32 v254, s0, 4
	s_addc_u32 s97, s89, 0
	v_mov_b32_e32 v112, v206
	v_writelane_b32 v254, s1, 5
	s_add_u32 s0, s88, 0xe00000
	s_addc_u32 s1, s89, 0
	v_writelane_b32 v254, s0, 6
	s_nop 0
	v_readfirstlane_b32 s3, v112
	v_writelane_b32 v254, s1, 7
	s_add_u32 s0, s88, 0x1000000
	s_addc_u32 s1, s89, 0
	v_writelane_b32 v254, s0, 8
	v_and_b32_e32 v2, 63, v112
	s_nop 0
	v_writelane_b32 v254, s1, 9
	s_add_u32 s0, s88, 0x1100000
	s_addc_u32 s1, s89, 0
	s_add_u32 s95, s88, 0x1300000
	v_writelane_b32 v254, s0, 10
	s_addc_u32 s30, s89, 0
	s_nop 0
	v_writelane_b32 v254, s1, 11
	s_add_u32 s0, s88, 0x3f00000
	v_writelane_b32 v254, s0, 12
	s_addc_u32 s0, s89, 0
	v_writelane_b32 v254, s0, 13
	s_lshl_b32 s0, s2, 3
	s_cmp_gt_i32 s90, 63
	s_cselect_b64 s[12:13], -1, 0
	s_sub_i32 s18, s90, 32
	s_cmp_ge_i32 s2, s18
	v_writelane_b32 v254, s0, 14
	s_cselect_b64 s[0:1], -1, 0
	s_and_b64 s[0:1], s[12:13], s[0:1]
	s_ashr_i32 s28, s3, 6
	s_andn2_b64 vcc, exec, s[0:1]
	s_mov_b64 s[0:1], -1
	v_writelane_b32 v254, s93, 15
	s_cbranch_vccz .LBB0_54
	v_writelane_b32 v254, s12, 16
	s_and_b64 s[0:1], s[12:13], exec
	s_mov_b32 s0, s18
	v_writelane_b32 v254, s13, 17
	v_writelane_b32 v254, s0, 18
	s_cselect_b32 s3, s18, s90
	s_nop 0
	v_writelane_b32 v254, s1, 19
	s_nop 0
	v_readlane_b32 s0, v254, 14
	s_add_i32 s13, s28, s0
	s_cmpk_gt_i32 s13, 0x48ff
	s_cbranch_scc1 .LBB0_33
	v_lshlrev_b32_e32 v10, 3, v2
	s_lshl_b32 s0, s28, 14
	v_lshrrev_b32_e32 v1, 5, v2
	v_and_b32_e32 v4, 31, v112
	v_lshrrev_b32_e32 v5, 3, v2
	v_and_b32_e32 v10, 56, v10
	s_add_i32 s0, s0, 0
	v_lshlrev_b32_e32 v6, 2, v4
	v_mul_u32_u24_e32 v3, 0x84, v1
	v_mul_u32_u24_e32 v14, 0x84, v10
	v_lshlrev_b32_e32 v26, 2, v5
	v_mov_b32_e32 v7, 0
	v_add3_u32 v3, s0, v3, v6
	v_add3_u32 v30, s0, v14, v26
	v_readlane_b32 s0, v254, 8
	v_lshlrev_b32_e32 v24, 1, v10
	v_mov_b32_e32 v25, v7
	v_readlane_b32 s1, v254, 9
	v_and_b32_e32 v11, 16, v26
	v_readlane_b32 s4, v254, 10
	v_lshl_add_u64 v[16:17], s[0:1], 0, v[24:25]
	v_readlane_b32 s0, v254, 6
	v_readlane_b32 s1, v254, 7
	v_readlane_b32 s5, v254, 11
	v_or_b32_e32 v31, v5, v26
	v_lshl_add_u64 v[20:21], s[0:1], 0, v[24:25]
	s_lshl_b32 s0, s2, 4
	s_lshl_b32 s1, s28, 1
	s_add_i32 s0, s0, s1
	v_or_b32_e32 v32, v11, v5
	s_add_i32 s15, s0, 0x17200
	s_lshl_b32 s0, s2, 5
	s_lshl_b32 s1, s28, 2
	s_lshl_b32 s14, s3, 3
	v_lshl_add_u64 v[8:9], s[84:85], 0, v[6:7]
	v_lshl_add_u64 v[12:13], s[4:5], 0, v[24:25]
	v_lshl_add_u64 v[14:15], s[80:81], 0, v[6:7]
	v_lshl_add_u64 v[18:19], s[82:83], 0, v[6:7]
	v_lshl_add_u64 v[22:23], s[56:57], 0, v[6:7]
	v_lshl_add_u64 v[24:25], s[96:97], 0, v[24:25]
	v_bitop3_b32 v33, v5, 19, v26 bitop3:0xc8
	v_or_b32_e32 v34, 0x8c, v26
	v_or_b32_e32 v35, 12, v26
	v_or_b32_e32 v36, 4, v32
	v_or_b32_e32 v37, 12, v31
	s_lshl_b32 s16, s3, 4
	s_add_i32 s17, s0, s1
	s_lshl_b32 s18, s3, 5
	s_movk_i32 s94, 0x2000
	s_movk_i32 s93, 0x4000
	s_mov_b32 s26, 0x10000
	s_mov_b32 s31, 0x16000
	v_add_u32_e32 v38, 0x400, v3
	v_add_u32_e32 v39, 0x800, v3
	v_add_u32_e32 v40, 0xc00, v3
	v_add_u32_e32 v41, 0x1000, v3
	v_add_u32_e32 v42, 0x1400, v3
	v_add_u32_e32 v43, 0x1800, v3
	v_add_u32_e32 v44, 0x1c00, v3
	v_mov_b32_e32 v45, 0x2000
	v_mov_b32_e32 v46, 0x6000
	v_mov_b32_e32 v47, 0x200
	v_mov_b32_e32 v48, 0x1000
	v_mov_b32_e32 v49, 0x3000
	v_mov_b32_e32 v50, 0x63
	s_mov_b32 s83, 0x26000
	s_mov_b32 s21, 0x2c000
	s_mov_b32 s27, 0x3c000
	s_movk_i32 s57, 0x5000
	s_mov_b32 s80, 0xb000
	s_mov_b32 s10, 0x1b000
	s_mov_b32 s11, 0x37000
	s_mov_b32 s82, 0x4d000
	s_mov_b32 s19, 0x6e000
	s_mov_b32 s12, 0x73000
	s_mov_b32 s20, 0x79000
	s_mov_b32 s84, 0x7e000
	s_mov_b32 s85, 0x84000
	s_mov_b32 s22, 0x89000
	s_mov_b32 s25, 0x8f000
	s_mov_b32 s56, 0x94000
	s_mov_b32 s23, 0x9a000
	s_mov_b32 s24, 0x9f000
	s_mov_b32 s29, 0xa5000
	s_mov_b32 s81, 0xaa000
	s_mov_b32 s1, 0
	s_branch .LBB0_10
